# speedup vs baseline: 1.0683x; 1.0683x over previous
; #define LDSP(p) ((__attribute__((address_space(3))) unsigned*)(p))
; #define SCAN_BAR() do { asm volatile("s_waitcnt lgkmcnt(0)" ::: "memory"); __builtin_amdgcn_s_barrier(); asm volatile("" ::: "memory"); } while (0)
; __device__ __forceinline__ void scan_phase(const ScanArgs& s, char* shm) {
;     ...
;       const int rr = lane >> 4, j = lane & 15, row = wid * 4 + rr;
;       float S0 = 0.f, S1 = 0.f, S2 = 0.f, S3 = 0.f, d1 = 0.f, ppv = 0.f, Gp = 0.f;
;       const unsigned lds0 = (unsigned)(size_t)LDSP(shm);
;       SCAN_BAR();
.LBB0_169:
	s_andn2_saveexec_b64 s[54:55], s[54:55]
	s_cbranch_execz .LBB0_126
	s_waitcnt lgkmcnt(0)
	s_barrier
	v_mov_b32_e32 v0, 0
	v_mov_b32_e32 v1, 0
	v_mov_b32_e32 v2, 0
	v_mov_b32_e32 v3, 0
	v_mov_b32_e32 v4, 0
	v_mov_b32_e32 v5, 0
	v_mov_b32_e32 v6, 0
	v_mov_b32_e32 v7, 0
	v_mov_b32_e32 v67, 0
	s_mov_b32 s49, 0
	s_mov_b32 s56, 0
	s_branch .LBB0_172

; __device__ __forceinline__ void scan_phase(const ScanArgs& s, char* shm) {
;     ...
;           float4* sr = (float4*)(shm + OFF_SRING + (c & 1) * (TC * 2048) + wid * 1024 + lane * 16);
;           const unsigned aj = lds0 + (unsigned)((c & 3) * VECBUF) + (unsigned)j * 16u, av = lds0 + (unsigned)((c & 3) * VECBUF) + 1024u + (unsigned)row * 8u;
;           f32x4 mkA, w4A, kaA, kmA, mkB, w4B, kaB, kmB, mkC, w4C, kaC, kmC; f32x2 vgA, vgB, vgC;
;     ...
;           SLOAD(A, 0); SLOAD(B, 1); SLOAD(C, 2);
;           SSTEP(A, 0); SSTEP(B, 1); SSTEP(C, 2); SSTEP(A, 3); SSTEP(B, 4); SSTEP(C, 5); SSTEP(A, 6); SSTEP(B, 7);
;           SSTEP(C, 8); SSTEP(A, 9); SSTEP(B, 10); SSTEP(C, 11); SSTEP(A, 12); SSTEP(B, 13); SSTEP(C, 14); SSTEP(A, 15);
.LBB0_172:
	s_cmpk_gt_u32 s56, 0x3ff
	s_cbranch_scc1 .LBB0_171
	s_and_b32 s57, s49, 0x8000
	v_add_u32_e32 v70, s57, v175
	s_and_b32 s57, s56, 3
	s_mulk_i32 s57, 0x4400
	v_or_b32_e32 v68, s57, v172
	v_add_u32_e32 v69, s57, v176
	ds_read_b128 v[12:15], v68 offset:0
	ds_read_b128 v[16:19], v68 offset:256
	ds_read_b128 v[20:23], v68 offset:512
	ds_read_b128 v[24:27], v68 offset:768
	ds_read_b64 v[60:61], v69 offset:0
	ds_read_b128 v[28:31], v68 offset:1088
	ds_read_b128 v[32:35], v68 offset:1344
	ds_read_b128 v[36:39], v68 offset:1600
	ds_read_b128 v[40:43], v68 offset:1856
	ds_read_b64 v[62:63], v69 offset:1088
	ds_read_b128 v[44:47], v68 offset:2176
	ds_read_b128 v[48:51], v68 offset:2432
	ds_read_b128 v[52:55], v68 offset:2688
	ds_read_b128 v[56:59], v68 offset:2944
	ds_read_b64 v[64:65], v69 offset:2176
	s_waitcnt lgkmcnt(10)
	v_add_f32_dpp v4, v7, v7 quad_perm:[1,0,3,2] row_mask:0xf bank_mask:0xf bound_ctrl:1
	v_pk_mul_f32 v[8:9], v[24:25], v[60:61] op_sel_hi:[1,0]
	v_pk_mul_f32 v[10:11], v[26:27], v[60:61] op_sel_hi:[1,0]
	v_add_f32_dpp v4, v4, v4 quad_perm:[2,3,0,1] row_mask:0xf bank_mask:0xf bound_ctrl:1
	v_pk_fma_f32 v[0:1], v[0:1], v[16:17], v[8:9]
	v_pk_fma_f32 v[2:3], v[2:3], v[18:19], v[10:11]
	v_add_f32_dpp v4, v4, v4 row_half_mirror row_mask:0xf bank_mask:0xf bound_ctrl:1
	v_pk_mul_f32 v[8:9], v[0:1], v[12:13]
	v_pk_fma_f32 v[8:9], v[2:3], v[14:15], v[8:9]
	v_add_f32_dpp v4, v4, v4 row_mirror row_mask:0xf bank_mask:0xf bound_ctrl:1
	v_add_f32_e32 v7, v8, v9
	v_fmac_f32_e32 v4, v6, v67
	v_pk_fma_f32 v[0:1], v[20:21], v[4:5], v[0:1] op_sel_hi:[1,0,1]
	v_pk_fma_f32 v[2:3], v[22:23], v[4:5], v[2:3] op_sel_hi:[1,0,1]
	ds_write_b128 v70, v[0:3] offset:0
	ds_read_b128 v[12:15], v68 offset:3264
	ds_read_b128 v[16:19], v68 offset:3520
	ds_read_b128 v[20:23], v68 offset:3776
	ds_read_b128 v[24:27], v68 offset:4032
	ds_read_b64 v[66:67], v69 offset:3264
	s_waitcnt lgkmcnt(11)
	v_add_f32_dpp v6, v7, v7 quad_perm:[1,0,3,2] row_mask:0xf bank_mask:0xf bound_ctrl:1
	v_pk_mul_f32 v[8:9], v[40:41], v[62:63] op_sel_hi:[1,0]
	v_pk_mul_f32 v[10:11], v[42:43], v[62:63] op_sel_hi:[1,0]
	v_add_f32_dpp v6, v6, v6 quad_perm:[2,3,0,1] row_mask:0xf bank_mask:0xf bound_ctrl:1
	v_pk_fma_f32 v[0:1], v[0:1], v[32:33], v[8:9]
	v_pk_fma_f32 v[2:3], v[2:3], v[34:35], v[10:11]
	v_add_f32_dpp v6, v6, v6 row_half_mirror row_mask:0xf bank_mask:0xf bound_ctrl:1
	v_pk_mul_f32 v[8:9], v[0:1], v[28:29]
	v_pk_fma_f32 v[8:9], v[2:3], v[30:31], v[8:9]
	v_add_f32_dpp v6, v6, v6 row_mirror row_mask:0xf bank_mask:0xf bound_ctrl:1
	v_add_f32_e32 v7, v8, v9
	v_fmac_f32_e32 v6, v4, v61
	v_pk_fma_f32 v[0:1], v[36:37], v[6:7], v[0:1] op_sel_hi:[1,0,1]
	v_pk_fma_f32 v[2:3], v[38:39], v[6:7], v[2:3] op_sel_hi:[1,0,1]
	ds_write_b128 v70, v[0:3] offset:2048
	ds_read_b128 v[28:31], v68 offset:4352
	ds_read_b128 v[32:35], v68 offset:4608
	ds_read_b128 v[36:39], v68 offset:4864
	ds_read_b128 v[40:43], v68 offset:5120
	ds_read_b64 v[60:61], v69 offset:4352
	s_waitcnt lgkmcnt(12)
	v_add_f32_dpp v4, v7, v7 quad_perm:[1,0,3,2] row_mask:0xf bank_mask:0xf bound_ctrl:1
	v_pk_mul_f32 v[8:9], v[56:57], v[64:65] op_sel_hi:[1,0]
	v_pk_mul_f32 v[10:11], v[58:59], v[64:65] op_sel_hi:[1,0]
	v_add_f32_dpp v4, v4, v4 quad_perm:[2,3,0,1] row_mask:0xf bank_mask:0xf bound_ctrl:1
	v_pk_fma_f32 v[0:1], v[0:1], v[48:49], v[8:9]
	v_pk_fma_f32 v[2:3], v[2:3], v[50:51], v[10:11]
	v_add_f32_dpp v4, v4, v4 row_half_mirror row_mask:0xf bank_mask:0xf bound_ctrl:1
	v_pk_mul_f32 v[8:9], v[0:1], v[44:45]
	v_pk_fma_f32 v[8:9], v[2:3], v[46:47], v[8:9]
	v_add_f32_dpp v4, v4, v4 row_mirror row_mask:0xf bank_mask:0xf bound_ctrl:1
	v_add_f32_e32 v7, v8, v9
	v_fmac_f32_e32 v4, v6, v63
	v_pk_fma_f32 v[0:1], v[52:53], v[4:5], v[0:1] op_sel_hi:[1,0,1]
	v_pk_fma_f32 v[2:3], v[54:55], v[4:5], v[2:3] op_sel_hi:[1,0,1]
	ds_write_b128 v70, v[0:3] offset:4096
	ds_read_b128 v[44:47], v68 offset:5440
	ds_read_b128 v[48:51], v68 offset:5696
	ds_read_b128 v[52:55], v68 offset:5952
	ds_read_b128 v[56:59], v68 offset:6208
	ds_read_b64 v[62:63], v69 offset:5440
	s_waitcnt lgkmcnt(12)
	v_add_f32_dpp v6, v7, v7 quad_perm:[1,0,3,2] row_mask:0xf bank_mask:0xf bound_ctrl:1
	v_pk_mul_f32 v[8:9], v[24:25], v[66:67] op_sel_hi:[1,0]
	v_pk_mul_f32 v[10:11], v[26:27], v[66:67] op_sel_hi:[1,0]
	v_add_f32_dpp v6, v6, v6 quad_perm:[2,3,0,1] row_mask:0xf bank_mask:0xf bound_ctrl:1
	v_pk_fma_f32 v[0:1], v[0:1], v[16:17], v[8:9]
	v_pk_fma_f32 v[2:3], v[2:3], v[18:19], v[10:11]
	v_add_f32_dpp v6, v6, v6 row_half_mirror row_mask:0xf bank_mask:0xf bound_ctrl:1
	v_pk_mul_f32 v[8:9], v[0:1], v[12:13]
	v_pk_fma_f32 v[8:9], v[2:3], v[14:15], v[8:9]
	v_add_f32_dpp v6, v6, v6 row_mirror row_mask:0xf bank_mask:0xf bound_ctrl:1
	v_add_f32_e32 v7, v8, v9
	v_fmac_f32_e32 v6, v4, v65
	v_pk_fma_f32 v[0:1], v[20:21], v[6:7], v[0:1] op_sel_hi:[1,0,1]
	v_pk_fma_f32 v[2:3], v[22:23], v[6:7], v[2:3] op_sel_hi:[1,0,1]
	ds_write_b128 v70, v[0:3] offset:6144
	ds_read_b128 v[12:15], v68 offset:6528
	ds_read_b128 v[16:19], v68 offset:6784
	ds_read_b128 v[20:23], v68 offset:7040
	ds_read_b128 v[24:27], v68 offset:7296
	ds_read_b64 v[64:65], v69 offset:6528
	s_waitcnt lgkmcnt(12)
; __device__ __forceinline__ void scan_phase(const ScanArgs& s, char* shm) {
;     ...
;           SLOAD(A, 0); SLOAD(B, 1); SLOAD(C, 2);
;           SSTEP(A, 0); SSTEP(B, 1); SSTEP(C, 2); SSTEP(A, 3); SSTEP(B, 4); SSTEP(C, 5); SSTEP(A, 6); SSTEP(B, 7);
;           SSTEP(C, 8); SSTEP(A, 9); SSTEP(B, 10); SSTEP(C, 11); SSTEP(A, 12); SSTEP(B, 13); SSTEP(C, 14); SSTEP(A, 15);
	v_add_f32_dpp v4, v7, v7 quad_perm:[1,0,3,2] row_mask:0xf bank_mask:0xf bound_ctrl:1
	v_pk_mul_f32 v[8:9], v[40:41], v[60:61] op_sel_hi:[1,0]
	v_pk_mul_f32 v[10:11], v[42:43], v[60:61] op_sel_hi:[1,0]
	v_add_f32_dpp v4, v4, v4 quad_perm:[2,3,0,1] row_mask:0xf bank_mask:0xf bound_ctrl:1
	v_pk_fma_f32 v[0:1], v[0:1], v[32:33], v[8:9]
	v_pk_fma_f32 v[2:3], v[2:3], v[34:35], v[10:11]
	v_add_f32_dpp v4, v4, v4 row_half_mirror row_mask:0xf bank_mask:0xf bound_ctrl:1
	v_pk_mul_f32 v[8:9], v[0:1], v[28:29]
	v_pk_fma_f32 v[8:9], v[2:3], v[30:31], v[8:9]
	v_add_f32_dpp v4, v4, v4 row_mirror row_mask:0xf bank_mask:0xf bound_ctrl:1
	v_add_f32_e32 v7, v8, v9
	v_fmac_f32_e32 v4, v6, v67
	v_pk_fma_f32 v[0:1], v[36:37], v[4:5], v[0:1] op_sel_hi:[1,0,1]
	v_pk_fma_f32 v[2:3], v[38:39], v[4:5], v[2:3] op_sel_hi:[1,0,1]
	ds_write_b128 v70, v[0:3] offset:8192
	ds_read_b128 v[28:31], v68 offset:7616
	ds_read_b128 v[32:35], v68 offset:7872
	ds_read_b128 v[36:39], v68 offset:8128
	ds_read_b128 v[40:43], v68 offset:8384
	ds_read_b64 v[66:67], v69 offset:7616
	s_waitcnt lgkmcnt(12)
	v_add_f32_dpp v6, v7, v7 quad_perm:[1,0,3,2] row_mask:0xf bank_mask:0xf bound_ctrl:1
	v_pk_mul_f32 v[8:9], v[56:57], v[62:63] op_sel_hi:[1,0]
	v_pk_mul_f32 v[10:11], v[58:59], v[62:63] op_sel_hi:[1,0]
	v_add_f32_dpp v6, v6, v6 quad_perm:[2,3,0,1] row_mask:0xf bank_mask:0xf bound_ctrl:1
	v_pk_fma_f32 v[0:1], v[0:1], v[48:49], v[8:9]
	v_pk_fma_f32 v[2:3], v[2:3], v[50:51], v[10:11]
	v_add_f32_dpp v6, v6, v6 row_half_mirror row_mask:0xf bank_mask:0xf bound_ctrl:1
	v_pk_mul_f32 v[8:9], v[0:1], v[44:45]
	v_pk_fma_f32 v[8:9], v[2:3], v[46:47], v[8:9]
	v_add_f32_dpp v6, v6, v6 row_mirror row_mask:0xf bank_mask:0xf bound_ctrl:1
	v_add_f32_e32 v7, v8, v9
	v_fmac_f32_e32 v6, v4, v61
	v_pk_fma_f32 v[0:1], v[52:53], v[6:7], v[0:1] op_sel_hi:[1,0,1]
	v_pk_fma_f32 v[2:3], v[54:55], v[6:7], v[2:3] op_sel_hi:[1,0,1]
	ds_write_b128 v70, v[0:3] offset:10240
	ds_read_b128 v[44:47], v68 offset:8704
	ds_read_b128 v[48:51], v68 offset:8960
	ds_read_b128 v[52:55], v68 offset:9216
	ds_read_b128 v[56:59], v68 offset:9472
	ds_read_b64 v[60:61], v69 offset:8704
	s_waitcnt lgkmcnt(12)
	v_add_f32_dpp v4, v7, v7 quad_perm:[1,0,3,2] row_mask:0xf bank_mask:0xf bound_ctrl:1
	v_pk_mul_f32 v[8:9], v[24:25], v[64:65] op_sel_hi:[1,0]
	v_pk_mul_f32 v[10:11], v[26:27], v[64:65] op_sel_hi:[1,0]
	v_add_f32_dpp v4, v4, v4 quad_perm:[2,3,0,1] row_mask:0xf bank_mask:0xf bound_ctrl:1
	v_pk_fma_f32 v[0:1], v[0:1], v[16:17], v[8:9]
	v_pk_fma_f32 v[2:3], v[2:3], v[18:19], v[10:11]
	v_add_f32_dpp v4, v4, v4 row_half_mirror row_mask:0xf bank_mask:0xf bound_ctrl:1
	v_pk_mul_f32 v[8:9], v[0:1], v[12:13]
	v_pk_fma_f32 v[8:9], v[2:3], v[14:15], v[8:9]
	v_add_f32_dpp v4, v4, v4 row_mirror row_mask:0xf bank_mask:0xf bound_ctrl:1
	v_add_f32_e32 v7, v8, v9
	v_fmac_f32_e32 v4, v6, v63
	v_pk_fma_f32 v[0:1], v[20:21], v[4:5], v[0:1] op_sel_hi:[1,0,1]
	v_pk_fma_f32 v[2:3], v[22:23], v[4:5], v[2:3] op_sel_hi:[1,0,1]
	ds_write_b128 v70, v[0:3] offset:12288
	ds_read_b128 v[12:15], v68 offset:9792
	ds_read_b128 v[16:19], v68 offset:10048
	ds_read_b128 v[20:23], v68 offset:10304
	ds_read_b128 v[24:27], v68 offset:10560
	ds_read_b64 v[62:63], v69 offset:9792
	s_waitcnt lgkmcnt(12)
	v_add_f32_dpp v6, v7, v7 quad_perm:[1,0,3,2] row_mask:0xf bank_mask:0xf bound_ctrl:1
	v_pk_mul_f32 v[8:9], v[40:41], v[66:67] op_sel_hi:[1,0]
	v_pk_mul_f32 v[10:11], v[42:43], v[66:67] op_sel_hi:[1,0]
	v_add_f32_dpp v6, v6, v6 quad_perm:[2,3,0,1] row_mask:0xf bank_mask:0xf bound_ctrl:1
	v_pk_fma_f32 v[0:1], v[0:1], v[32:33], v[8:9]
	v_pk_fma_f32 v[2:3], v[2:3], v[34:35], v[10:11]
	v_add_f32_dpp v6, v6, v6 row_half_mirror row_mask:0xf bank_mask:0xf bound_ctrl:1
	v_pk_mul_f32 v[8:9], v[0:1], v[28:29]
	v_pk_fma_f32 v[8:9], v[2:3], v[30:31], v[8:9]
	v_add_f32_dpp v6, v6, v6 row_mirror row_mask:0xf bank_mask:0xf bound_ctrl:1
	v_add_f32_e32 v7, v8, v9
	v_fmac_f32_e32 v6, v4, v65
	v_pk_fma_f32 v[0:1], v[36:37], v[6:7], v[0:1] op_sel_hi:[1,0,1]
	v_pk_fma_f32 v[2:3], v[38:39], v[6:7], v[2:3] op_sel_hi:[1,0,1]
	ds_write_b128 v70, v[0:3] offset:14336
	ds_read_b128 v[28:31], v68 offset:10880
	ds_read_b128 v[32:35], v68 offset:11136
	ds_read_b128 v[36:39], v68 offset:11392
	ds_read_b128 v[40:43], v68 offset:11648
	ds_read_b64 v[64:65], v69 offset:10880
	s_waitcnt lgkmcnt(12)
	v_add_f32_dpp v4, v7, v7 quad_perm:[1,0,3,2] row_mask:0xf bank_mask:0xf bound_ctrl:1
	v_pk_mul_f32 v[8:9], v[56:57], v[60:61] op_sel_hi:[1,0]
	v_pk_mul_f32 v[10:11], v[58:59], v[60:61] op_sel_hi:[1,0]
	v_add_f32_dpp v4, v4, v4 quad_perm:[2,3,0,1] row_mask:0xf bank_mask:0xf bound_ctrl:1
	v_pk_fma_f32 v[0:1], v[0:1], v[48:49], v[8:9]
	v_pk_fma_f32 v[2:3], v[2:3], v[50:51], v[10:11]
	v_add_f32_dpp v4, v4, v4 row_half_mirror row_mask:0xf bank_mask:0xf bound_ctrl:1
	v_pk_mul_f32 v[8:9], v[0:1], v[44:45]
	v_pk_fma_f32 v[8:9], v[2:3], v[46:47], v[8:9]
	v_add_f32_dpp v4, v4, v4 row_mirror row_mask:0xf bank_mask:0xf bound_ctrl:1
	v_add_f32_e32 v7, v8, v9
	v_fmac_f32_e32 v4, v6, v67
	v_pk_fma_f32 v[0:1], v[52:53], v[4:5], v[0:1] op_sel_hi:[1,0,1]
	v_pk_fma_f32 v[2:3], v[54:55], v[4:5], v[2:3] op_sel_hi:[1,0,1]
	ds_write_b128 v70, v[0:3] offset:16384
	ds_read_b128 v[44:47], v68 offset:11968
	ds_read_b128 v[48:51], v68 offset:12224
	ds_read_b128 v[52:55], v68 offset:12480
	ds_read_b128 v[56:59], v68 offset:12736
	ds_read_b64 v[66:67], v69 offset:11968
	s_waitcnt lgkmcnt(12)
; #define SCAN_BAR() do { asm volatile("s_waitcnt lgkmcnt(0)" ::: "memory"); __builtin_amdgcn_s_barrier(); asm volatile("" ::: "memory"); } while (0)
; __device__ __forceinline__ void scan_phase(const ScanArgs& s, char* shm) {
;     ...
;           SLOAD(A, 0); SLOAD(B, 1); SLOAD(C, 2);
;           SSTEP(A, 0); SSTEP(B, 1); SSTEP(C, 2); SSTEP(A, 3); SSTEP(B, 4); SSTEP(C, 5); SSTEP(A, 6); SSTEP(B, 7);
;           SSTEP(C, 8); SSTEP(A, 9); SSTEP(B, 10); SSTEP(C, 11); SSTEP(A, 12); SSTEP(B, 13); SSTEP(C, 14); SSTEP(A, 15);
;     ...
;         }
;         SCAN_BAR();
	v_add_f32_dpp v6, v7, v7 quad_perm:[1,0,3,2] row_mask:0xf bank_mask:0xf bound_ctrl:1
	v_pk_mul_f32 v[8:9], v[24:25], v[62:63] op_sel_hi:[1,0]
	v_pk_mul_f32 v[10:11], v[26:27], v[62:63] op_sel_hi:[1,0]
	v_add_f32_dpp v6, v6, v6 quad_perm:[2,3,0,1] row_mask:0xf bank_mask:0xf bound_ctrl:1
	v_pk_fma_f32 v[0:1], v[0:1], v[16:17], v[8:9]
	v_pk_fma_f32 v[2:3], v[2:3], v[18:19], v[10:11]
	v_add_f32_dpp v6, v6, v6 row_half_mirror row_mask:0xf bank_mask:0xf bound_ctrl:1
	v_pk_mul_f32 v[8:9], v[0:1], v[12:13]
	v_pk_fma_f32 v[8:9], v[2:3], v[14:15], v[8:9]
	v_add_f32_dpp v6, v6, v6 row_mirror row_mask:0xf bank_mask:0xf bound_ctrl:1
	v_add_f32_e32 v7, v8, v9
	v_fmac_f32_e32 v6, v4, v61
	v_pk_fma_f32 v[0:1], v[20:21], v[6:7], v[0:1] op_sel_hi:[1,0,1]
	v_pk_fma_f32 v[2:3], v[22:23], v[6:7], v[2:3] op_sel_hi:[1,0,1]
	ds_write_b128 v70, v[0:3] offset:18432
	ds_read_b128 v[12:15], v68 offset:13056
	ds_read_b128 v[16:19], v68 offset:13312
	ds_read_b128 v[20:23], v68 offset:13568
	ds_read_b128 v[24:27], v68 offset:13824
	ds_read_b64 v[60:61], v69 offset:13056
	s_waitcnt lgkmcnt(12)
	v_add_f32_dpp v4, v7, v7 quad_perm:[1,0,3,2] row_mask:0xf bank_mask:0xf bound_ctrl:1
	v_pk_mul_f32 v[8:9], v[40:41], v[64:65] op_sel_hi:[1,0]
	v_pk_mul_f32 v[10:11], v[42:43], v[64:65] op_sel_hi:[1,0]
	v_add_f32_dpp v4, v4, v4 quad_perm:[2,3,0,1] row_mask:0xf bank_mask:0xf bound_ctrl:1
	v_pk_fma_f32 v[0:1], v[0:1], v[32:33], v[8:9]
	v_pk_fma_f32 v[2:3], v[2:3], v[34:35], v[10:11]
	v_add_f32_dpp v4, v4, v4 row_half_mirror row_mask:0xf bank_mask:0xf bound_ctrl:1
	v_pk_mul_f32 v[8:9], v[0:1], v[28:29]
	v_pk_fma_f32 v[8:9], v[2:3], v[30:31], v[8:9]
	v_add_f32_dpp v4, v4, v4 row_mirror row_mask:0xf bank_mask:0xf bound_ctrl:1
	v_add_f32_e32 v7, v8, v9
	v_fmac_f32_e32 v4, v6, v63
	v_pk_fma_f32 v[0:1], v[36:37], v[4:5], v[0:1] op_sel_hi:[1,0,1]
	v_pk_fma_f32 v[2:3], v[38:39], v[4:5], v[2:3] op_sel_hi:[1,0,1]
	ds_write_b128 v70, v[0:3] offset:20480
	ds_read_b128 v[28:31], v68 offset:14144
	ds_read_b128 v[32:35], v68 offset:14400
	ds_read_b128 v[36:39], v68 offset:14656
	ds_read_b128 v[40:43], v68 offset:14912
	ds_read_b64 v[62:63], v69 offset:14144
	s_waitcnt lgkmcnt(12)
	v_add_f32_dpp v6, v7, v7 quad_perm:[1,0,3,2] row_mask:0xf bank_mask:0xf bound_ctrl:1
	v_pk_mul_f32 v[8:9], v[56:57], v[66:67] op_sel_hi:[1,0]
	v_pk_mul_f32 v[10:11], v[58:59], v[66:67] op_sel_hi:[1,0]
	v_add_f32_dpp v6, v6, v6 quad_perm:[2,3,0,1] row_mask:0xf bank_mask:0xf bound_ctrl:1
	v_pk_fma_f32 v[0:1], v[0:1], v[48:49], v[8:9]
	v_pk_fma_f32 v[2:3], v[2:3], v[50:51], v[10:11]
	v_add_f32_dpp v6, v6, v6 row_half_mirror row_mask:0xf bank_mask:0xf bound_ctrl:1
	v_pk_mul_f32 v[8:9], v[0:1], v[44:45]
	v_pk_fma_f32 v[8:9], v[2:3], v[46:47], v[8:9]
	v_add_f32_dpp v6, v6, v6 row_mirror row_mask:0xf bank_mask:0xf bound_ctrl:1
	v_add_f32_e32 v7, v8, v9
	v_fmac_f32_e32 v6, v4, v65
	v_pk_fma_f32 v[0:1], v[52:53], v[6:7], v[0:1] op_sel_hi:[1,0,1]
	v_pk_fma_f32 v[2:3], v[54:55], v[6:7], v[2:3] op_sel_hi:[1,0,1]
	ds_write_b128 v70, v[0:3] offset:22528
	ds_read_b128 v[44:47], v68 offset:15232
	ds_read_b128 v[48:51], v68 offset:15488
	ds_read_b128 v[52:55], v68 offset:15744
	ds_read_b128 v[56:59], v68 offset:16000
	ds_read_b64 v[64:65], v69 offset:15232
	s_waitcnt lgkmcnt(12)
	v_add_f32_dpp v4, v7, v7 quad_perm:[1,0,3,2] row_mask:0xf bank_mask:0xf bound_ctrl:1
	v_pk_mul_f32 v[8:9], v[24:25], v[60:61] op_sel_hi:[1,0]
	v_pk_mul_f32 v[10:11], v[26:27], v[60:61] op_sel_hi:[1,0]
	v_add_f32_dpp v4, v4, v4 quad_perm:[2,3,0,1] row_mask:0xf bank_mask:0xf bound_ctrl:1
	v_pk_fma_f32 v[0:1], v[0:1], v[16:17], v[8:9]
	v_pk_fma_f32 v[2:3], v[2:3], v[18:19], v[10:11]
	v_add_f32_dpp v4, v4, v4 row_half_mirror row_mask:0xf bank_mask:0xf bound_ctrl:1
	v_pk_mul_f32 v[8:9], v[0:1], v[12:13]
	v_pk_fma_f32 v[8:9], v[2:3], v[14:15], v[8:9]
	v_add_f32_dpp v4, v4, v4 row_mirror row_mask:0xf bank_mask:0xf bound_ctrl:1
	v_add_f32_e32 v7, v8, v9
	v_fmac_f32_e32 v4, v6, v67
	v_pk_fma_f32 v[0:1], v[20:21], v[4:5], v[0:1] op_sel_hi:[1,0,1]
	v_pk_fma_f32 v[2:3], v[22:23], v[4:5], v[2:3] op_sel_hi:[1,0,1]
	ds_write_b128 v70, v[0:3] offset:24576
	ds_read_b128 v[12:15], v68 offset:16320
	ds_read_b128 v[16:19], v68 offset:16576
	ds_read_b128 v[20:23], v68 offset:16832
	ds_read_b128 v[24:27], v68 offset:17088
	ds_read_b64 v[66:67], v69 offset:16320
	s_waitcnt lgkmcnt(12)
	v_add_f32_dpp v6, v7, v7 quad_perm:[1,0,3,2] row_mask:0xf bank_mask:0xf bound_ctrl:1
	v_pk_mul_f32 v[8:9], v[40:41], v[62:63] op_sel_hi:[1,0]
	v_pk_mul_f32 v[10:11], v[42:43], v[62:63] op_sel_hi:[1,0]
	v_add_f32_dpp v6, v6, v6 quad_perm:[2,3,0,1] row_mask:0xf bank_mask:0xf bound_ctrl:1
	v_pk_fma_f32 v[0:1], v[0:1], v[32:33], v[8:9]
	v_pk_fma_f32 v[2:3], v[2:3], v[34:35], v[10:11]
	v_add_f32_dpp v6, v6, v6 row_half_mirror row_mask:0xf bank_mask:0xf bound_ctrl:1
	v_pk_mul_f32 v[8:9], v[0:1], v[28:29]
	v_pk_fma_f32 v[8:9], v[2:3], v[30:31], v[8:9]
	v_add_f32_dpp v6, v6, v6 row_mirror row_mask:0xf bank_mask:0xf bound_ctrl:1
	v_add_f32_e32 v7, v8, v9
	v_fmac_f32_e32 v6, v4, v61
	v_pk_fma_f32 v[0:1], v[36:37], v[6:7], v[0:1] op_sel_hi:[1,0,1]
	v_pk_fma_f32 v[2:3], v[38:39], v[6:7], v[2:3] op_sel_hi:[1,0,1]
	ds_write_b128 v70, v[0:3] offset:26624
	s_waitcnt lgkmcnt(7)
	v_add_f32_dpp v4, v7, v7 quad_perm:[1,0,3,2] row_mask:0xf bank_mask:0xf bound_ctrl:1
	v_pk_mul_f32 v[8:9], v[56:57], v[64:65] op_sel_hi:[1,0]
	v_pk_mul_f32 v[10:11], v[58:59], v[64:65] op_sel_hi:[1,0]
	v_add_f32_dpp v4, v4, v4 quad_perm:[2,3,0,1] row_mask:0xf bank_mask:0xf bound_ctrl:1
	v_pk_fma_f32 v[0:1], v[0:1], v[48:49], v[8:9]
	v_pk_fma_f32 v[2:3], v[2:3], v[50:51], v[10:11]
	v_add_f32_dpp v4, v4, v4 row_half_mirror row_mask:0xf bank_mask:0xf bound_ctrl:1
	v_pk_mul_f32 v[8:9], v[0:1], v[44:45]
	v_pk_fma_f32 v[8:9], v[2:3], v[46:47], v[8:9]
	v_add_f32_dpp v4, v4, v4 row_mirror row_mask:0xf bank_mask:0xf bound_ctrl:1
	v_add_f32_e32 v7, v8, v9
	v_fmac_f32_e32 v4, v6, v63
	v_pk_fma_f32 v[0:1], v[52:53], v[4:5], v[0:1] op_sel_hi:[1,0,1]
	v_pk_fma_f32 v[2:3], v[54:55], v[4:5], v[2:3] op_sel_hi:[1,0,1]
	ds_write_b128 v70, v[0:3] offset:28672
	s_waitcnt lgkmcnt(2)
	v_add_f32_dpp v6, v7, v7 quad_perm:[1,0,3,2] row_mask:0xf bank_mask:0xf bound_ctrl:1
	v_pk_mul_f32 v[8:9], v[24:25], v[66:67] op_sel_hi:[1,0]
	v_pk_mul_f32 v[10:11], v[26:27], v[66:67] op_sel_hi:[1,0]
	v_add_f32_dpp v6, v6, v6 quad_perm:[2,3,0,1] row_mask:0xf bank_mask:0xf bound_ctrl:1
	v_pk_fma_f32 v[0:1], v[0:1], v[16:17], v[8:9]
	v_pk_fma_f32 v[2:3], v[2:3], v[18:19], v[10:11]
	v_add_f32_dpp v6, v6, v6 row_half_mirror row_mask:0xf bank_mask:0xf bound_ctrl:1
	v_pk_mul_f32 v[8:9], v[0:1], v[12:13]
	v_pk_fma_f32 v[8:9], v[2:3], v[14:15], v[8:9]
	v_add_f32_dpp v6, v6, v6 row_mirror row_mask:0xf bank_mask:0xf bound_ctrl:1
	v_add_f32_e32 v7, v8, v9
	v_fmac_f32_e32 v6, v4, v65
	v_pk_fma_f32 v[0:1], v[20:21], v[6:7], v[0:1] op_sel_hi:[1,0,1]
	v_pk_fma_f32 v[2:3], v[22:23], v[6:7], v[2:3] op_sel_hi:[1,0,1]
	ds_write_b128 v70, v[0:3] offset:30720
	s_branch .LBB0_171
